# sample diff-attention loop also software-pipelined (same structure as prompt loop)
# speedup vs baseline: 1.0087x; 1.0006x over previous
; __device__ __forceinline__ int pi32(int r) { return (r & ~12) | ((r & 4) << 1) | ((r & 8) >> 1); }
; #define AT_DMA(tr) do { const unsigned sb_ = (unsigned)__builtin_amdgcn_readfirstlane(dk + (((tr) & (NSTG - 1)) * STAGE)); const size_t ko_ = (size_t)(tr) * 26 * 4096, vo_ = (size_t)(tr) * 640 * 64; \
;         glds16(kg + ko_, sb_ + OFF_K0); if (!WIN) glds16(kg + ko_ + 4096, sb_ + OFF_K1); glds16(vg + vo_, sb_ + OFF_V); if (!WIN) glds16(vg + vo_ + 64 * 64, sb_ + OFF_V + 8192); } while (0)
; template <bool WIN> ...
;     ...
;     const bf16_t* kg = QK + ((size_t)((seq_base >> 6) + t_lo) * 26 * 64 + drow) * 64 + dch * 8 + kcol0 * 64;
;     const bf16_t* vg = VT + ((size_t)((seq_base >> 6) + t_lo) * 640 + vrow0 + drow) * 64 + dch * 8;
;     const unsigned dk = ldsb + wid * 1024;
;     ...
;     constexpr int NPW = WIN ? 2 : 4;
;     bf16x8 qfr[4];
;     { const int qrow = seq_base + qw + l31; const bf16_t* qp = QK + ((size_t)((qrow >> 6) * 26 + (qcol >> 6)) * 64 + (qrow & 63)) * 64 + hi * 8;
; #pragma unroll
;       for (int ds = 0; ds < 4; ++ds) qfr[ds] = *(const bf16x8*)(qp + ds * 16); }
;     ...
;     AT_DMA(0); if (NT > 1) AT_DMA(1); if (NT > 2) AT_DMA(2);
;     constexpr float THR = 8.0f;
;     float m_ref = WIN ? sinkp[2 * hsel + half] * LOG2E : 0.f;
;     float l_run = (WIN && hi == 0) ? 1.f : 0.f;
;     float cbase = 0.f;
;     f32x16 cvec;
; #pragma unroll
;     for (int r = 0; r < 16; ++r) cvec[r] = cbase - m_ref;
;     f32x16 o[NDB];
; #pragma unroll
;     for (int db = 0; db < NDB; ++db)
; #pragma unroll
;         for (int r = 0; r < 16; ++r) o[db][r] = 0.f;
;     const int krow = pi32(l31), fK = (krow >> 1) & 7, fV = (l31 >> 1) & 7;
;     int kx[4], vx[4];
; #pragma unroll
;     for (int c = 0; c < 4; ++c) { kx[c] = (WIN ? OFF_K0 : (half ? OFF_K1 : OFF_K0)) + krow * 128 + (((2 * c + hi) ^ fK) << 4); vx[c] = OFF_V + l31 * 128 + (((2 * c + hi) ^ fV) << 4); }
.LBB0_268:
	v_readfirstlane_b32 s33, v230
	s_lshl_b32 s26, s25, 13
	s_bfe_u32 s27, s33, 0x20006
	s_add_i32 s26, s26, s23
	s_lshl_b32 s28, s27, 5
	s_and_b32 s26, s26, 0xfffff800
	s_or_b32 s28, s28, s22
	s_add_i32 s29, s26, 0x10000
	s_lshr_b32 s26, s33, 8
	v_or_b32_e32 v10, s28, v185
	v_or_b32_e32 v170, s29, v10
	s_add_i32 s30, s26, s66
	v_ashrrev_i32_e32 v2, 6, v170
	v_mov_b32_e32 v0, s30
	v_mad_u64_u32 v[2:3], s[30:31], v2, 26, v[0:1]
	v_ashrrev_i32_e32 v3, 31, v2
	v_lshlrev_b64 v[2:3], 13, v[2:3]
	v_lshlrev_b32_e32 v0, 7, v10
	v_lshl_add_u64 v[2:3], s[6:7], 0, v[2:3]
	v_and_b32_e32 v4, 0x1f80, v0
	v_mov_b32_e32 v5, v1
	v_lshl_add_u64 v[2:3], v[2:3], 0, v[4:5]
	v_lshl_add_u64 v[2:3], v[2:3], 0, v[164:165]
	global_load_dwordx4 v[114:117], v[2:3], off offset:96
	global_load_dwordx4 v[118:121], v[2:3], off offset:64
	global_load_dwordx4 v[122:125], v[2:3], off offset:32
	global_load_dwordx4 v[126:129], v[2:3], off
	s_lshr_b32 s62, s33, 6
	s_lshr_b32 s30, s33, 4
	v_lshl_or_b32 v0, s62, 3, v188
	s_and_b32 s30, s30, 4
	s_ashr_i32 s76, s29, 6
	v_bitop3_b32 v4, s30, v186, v189 bitop3:0x36
	v_mad_i64_i32 v[2:3], s[30:31], s76, v194, v[0:1]
	v_lshlrev_b64 v[2:3], 7, v[2:3]
	v_lshl_add_u64 v[2:3], s[6:7], 0, v[2:3]
	v_lshlrev_b32_e32 v4, 4, v4
	s_mul_hi_i32 s31, s76, 0x280
	s_mul_i32 s30, s76, 0x280
	v_lshl_add_u64 v[2:3], v[2:3], 0, v[4:5]
	s_or_b64 s[30:31], s[30:31], s[12:13]
	v_lshl_add_u64 v[2:3], v[2:3], 0, s[18:19]
	v_lshl_add_u64 v[6:7], s[30:31], 0, v[0:1]
	s_lshl_b32 s29, s62, 10
	v_lshlrev_b64 v[6:7], 7, v[6:7]
	v_lshl_add_u64 v[8:9], v[2:3], 0, s[36:37]
	s_add_i32 s29, s29, 0
	s_mov_b32 s30, m0
	s_mov_b32 m0, s29
	s_nop 0
	global_load_lds_dwordx4 v[8:9], off
	s_mov_b32 m0, s30
	v_lshl_add_u64 v[6:7], s[4:5], 0, v[6:7]
	v_lshl_add_u64 v[8:9], v[2:3], 0, s[38:39]
	s_add_i32 s30, s29, 0x2000
	s_mov_b32 s31, m0
	s_mov_b32 m0, s30
	s_nop 0
	global_load_lds_dwordx4 v[8:9], off
	s_mov_b32 m0, s31
	v_lshl_add_u64 v[6:7], v[6:7], 0, v[4:5]
	s_add_i32 s30, s29, 0x4000
	s_mov_b32 s31, m0
	s_mov_b32 m0, s30
	s_nop 0
	global_load_lds_dwordx4 v[6:7], off
	s_mov_b32 m0, s31
	v_lshl_add_u64 v[8:9], v[6:7], 0, s[40:41]
	s_add_i32 s30, s29, 0x6000
	s_mov_b32 s31, m0
	s_mov_b32 m0, s30
	s_nop 0
	global_load_lds_dwordx4 v[8:9], off
	s_mov_b32 m0, s31
	s_add_i32 s30, s29, 0x8000
	v_lshl_add_u64 v[8:9], v[2:3], 0, s[42:43]
	s_mov_b32 s31, m0
	s_mov_b32 m0, s30
	s_nop 0
	global_load_lds_dwordx4 v[8:9], off
	s_mov_b32 m0, s31
	v_lshl_add_u64 v[8:9], v[2:3], 0, s[46:47]
	s_add_i32 s30, s29, 0xa000
	s_mov_b32 s31, m0
	s_mov_b32 m0, s30
	s_nop 0
	global_load_lds_dwordx4 v[8:9], off
	s_mov_b32 m0, s31
	v_lshl_add_u64 v[8:9], v[6:7], 0, s[48:49]
	s_add_i32 s30, s29, 0xc000
	s_mov_b32 s31, m0
	s_mov_b32 m0, s30
	s_nop 0
	global_load_lds_dwordx4 v[8:9], off
	s_mov_b32 m0, s31
	v_lshl_add_u64 v[8:9], v[6:7], 0, s[50:51]
	s_add_i32 s30, s29, 0xe000
	s_mov_b32 s31, m0
	s_mov_b32 m0, s30
	s_nop 0
	global_load_lds_dwordx4 v[8:9], off
	s_mov_b32 m0, s31
	s_add_i32 s30, s29, 0x10000
	v_lshl_add_u64 v[8:9], v[2:3], 0, s[52:53]
	s_mov_b32 s31, m0
	s_mov_b32 m0, s30
	s_nop 0
	global_load_lds_dwordx4 v[8:9], off
	s_mov_b32 m0, s31
	v_lshl_add_u64 v[2:3], v[2:3], 0, s[54:55]
	s_add_i32 s30, s29, 0x12000
	s_mov_b32 s31, m0
	s_mov_b32 m0, s30
	s_nop 0
	global_load_lds_dwordx4 v[2:3], off
	s_mov_b32 m0, s31
	v_lshl_add_u64 v[2:3], v[6:7], 0, s[56:57]
	s_add_i32 s30, s29, 0x14000
	v_lshl_add_u64 v[2:3], v[6:7], 0, s[58:59]
	s_add_i32 s30, s29, 0x16000
	ds_read_b32 v2, v197 offset:14336
	ds_read_b32 v3, v197 offset:16124
	s_cmpk_lt_u32 s33, 0x100
	s_cselect_b64 s[62:63], -1, 0
	s_and_b64 s[30:31], s[62:63], exec
	s_cselect_b32 s30, 0, 0x2000
	v_or_b32_e32 v162, s30, v177
	s_waitcnt lgkmcnt(1)
	v_readfirstlane_b32 s30, v2
	s_waitcnt lgkmcnt(0)
	v_readfirstlane_b32 s31, v3
	v_lshlrev_b64 v[2:3], 7, v[0:1]
	v_mad_i64_i32 v[6:7], s[64:65], s76, v198, v[2:3]
	v_mad_i64_i32 v[2:3], s[64:65], s76, v199, v[2:3]
	v_or_b32_e32 v6, v6, v4
	v_or_b32_e32 v2, v2, v4
	v_lshlrev_b32_e32 v0, 2, v10
	v_mov_b32_e32 v14, v1
	v_mov_b32_e32 v15, v1
	v_lshl_add_u64 v[172:173], s[20:21], 0, v[6:7]
	v_lshl_add_u64 v[174:175], s[16:17], 0, v[2:3]
	v_sub_u32_e32 v171, v195, v0
	v_mov_b32_e32 v0, v1
	v_mov_b32_e32 v2, v1
	v_mov_b32_e32 v3, v1
	v_mov_b32_e32 v4, v1
	v_mov_b32_e32 v6, v1
	v_mov_b32_e32 v7, v1
	v_mov_b32_e32 v8, v1
	v_mov_b32_e32 v9, v1
	v_mov_b32_e32 v10, v1
	v_mov_b32_e32 v11, v1
	v_mov_b32_e32 v12, v1
	v_mov_b32_e32 v13, v1
	v_mov_b64_e32 v[64:65], v[14:15]
	v_mov_b64_e32 v[48:49], v[14:15]
	v_mov_b64_e32 v[32:33], v[14:15]
	v_mov_b64_e32 v[62:63], v[12:13]
	v_mov_b64_e32 v[60:61], v[10:11]
	v_mov_b64_e32 v[58:59], v[8:9]
	v_mov_b64_e32 v[56:57], v[6:7]
	v_mov_b64_e32 v[54:55], v[4:5]
	v_mov_b64_e32 v[52:53], v[2:3]
	v_mov_b64_e32 v[50:51], v[0:1]
	v_mov_b64_e32 v[46:47], v[12:13]
	v_mov_b64_e32 v[44:45], v[10:11]
	v_mov_b64_e32 v[42:43], v[8:9]
	v_mov_b64_e32 v[40:41], v[6:7]
	v_mov_b64_e32 v[38:39], v[4:5]
	v_mov_b64_e32 v[36:37], v[2:3]
	v_mov_b64_e32 v[34:35], v[0:1]
	v_mov_b64_e32 v[30:31], v[12:13]
	v_mov_b64_e32 v[28:29], v[10:11]
	v_mov_b64_e32 v[26:27], v[8:9]
	v_mov_b64_e32 v[24:25], v[6:7]
	v_mov_b64_e32 v[22:23], v[4:5]
	v_mov_b64_e32 v[20:21], v[2:3]
	v_mov_b64_e32 v[18:19], v[0:1]
	v_mov_b64_e32 v[16:17], v[14:15]
	s_add_i32 s33, s28, 0x9f
	s_add_i32 s67, s28, 0xffffff41
	s_mov_b32 s76, 0
	s_mov_b32 s77, 0
	s_mov_b32 s78, 0x10000
	v_mov_b64_e32 v[14:15], v[12:13]
	v_mov_b64_e32 v[12:13], v[10:11]
	v_mov_b64_e32 v[10:11], v[8:9]
	v_mov_b64_e32 v[8:9], v[6:7]
	v_mov_b64_e32 v[6:7], v[4:5]
	v_mov_b64_e32 v[4:5], v[2:3]
	v_mov_b64_e32 v[2:3], v[0:1]
	v_mov_b32_e32 v0, 0
	v_mov_b32_e32 v201, 0
	v_mov_b32_e32 v202, 0
	s_mov_b32 s79, 0
	v_mov_b32_e32 v66, 0
	v_mov_b32_e32 v67, v1
	v_mov_b32_e32 v68, v1
	v_mov_b32_e32 v69, v1
	v_mov_b32_e32 v70, v1
	v_mov_b32_e32 v71, v1
	v_mov_b32_e32 v72, v1
	v_mov_b32_e32 v73, v1
	v_mov_b32_e32 v74, v1
	v_mov_b32_e32 v75, v1
	v_mov_b32_e32 v76, v1
	v_mov_b32_e32 v77, v1
	v_mov_b32_e32 v78, v1
	v_mov_b32_e32 v79, v1
	v_mov_b32_e32 v80, v1
	v_mov_b32_e32 v81, v1
	s_mov_b32 s98, 0xfffec000
	s_mov_b32 s99, -1
	v_lshl_add_u64 v[172:173], v[172:173], 0, s[98:99]
	s_mov_b32 s98, 0xfffcc000
	s_waitcnt vmcnt(10)
	s_branch .LSPs_top
; #define ALAS __attribute__((address_space(3)))
; template <bool WIN> ...
;     ...
;     for (int tr = 0; tr < NT; ++tr) {
;         if (tr + 2 < NT) wait_bar<2 * NPW>(); else if (tr + 1 < NT) wait_bar<NPW>(); else wait_bar<0>();
;         if (tr + 3 < NT) AT_DMA(tr + 3);
;         const int k0 = (t_lo + tr) * 64;
;         const bool skip = WIN && (k0 > qw + 31 + 128 || k0 + 63 < qw - 128);
;         if (!skip) {
;             const bool near = WIN || ((k0 - (qw + 31)) < 128 && (qw - (k0 + 63)) < 128);
;             const float cinit = near ? 0.f : (k0 > qw ? cfar_hi : cfar_lo);
;             if (__builtin_expect(cinit != cbase, 0)) { cbase = cinit; asm volatile("" ::: "memory");
; #pragma unroll
;                 for (int r = 0; r < 16; ++r) cvec[r] = cbase - m_ref; }
;             f32x16 s0, s1;
;             const ALAS unsigned char* sb = lds + (tr & (NSTG - 1)) * STAGE;
;             {
;                 bf16x8 ka[8];
; #pragma unroll
;                 for (int ds = 0; ds < 4; ++ds) { ka[2 * ds] = *(const ALAS bf16x8*)(sb + kx[ds]); ka[2 * ds + 1] = *(const ALAS bf16x8*)(sb + kx[ds] + 4096); }
;                 __builtin_amdgcn_sched_barrier(0);
;                 s0 = __builtin_amdgcn_mfma_f32_32x32x16_bf16(ka[0], qf(0), cvec, 0, 0, 0);
;                 s1 = __builtin_amdgcn_mfma_f32_32x32x16_bf16(ka[1], qf(0), cvec, 0, 0, 0);
; #pragma unroll
;                 for (int ds = 1; ds < 4; ++ds) {
;                     s0 = __builtin_amdgcn_mfma_f32_32x32x16_bf16(ka[2 * ds], qf(ds), s0, 0, 0, 0);
;                     s1 = __builtin_amdgcn_mfma_f32_32x32x16_bf16(ka[2 * ds + 1], qf(ds), s1, 0, 0, 0);
;                 }
;             }
;             bf16x8 va[2 * NDB], vc[2 * NDB];
; #pragma unroll
;             for (int kk = 0; kk < 2; ++kk)
; #pragma unroll
;                 for (int db = 0; db < NDB; ++db) va[kk * NDB + db] = *(const ALAS bf16x8*)(sb + vx[kk] + db * 4096);
;             __builtin_amdgcn_sched_barrier(0);
;             if (near) {
;                 const ALAS float* lb = lut + (k0 + 8 * hi - qabs + LUTC);
; #pragma unroll
;                 for (int r = 0; r < 16; ++r) { s0[r] += lb[16 * (r >> 3) + (r & 7)]; s1[r] += lb[32 + 16 * (r >> 3) + (r & 7)];
;                     if ((r & 7) == 7) __builtin_amdgcn_sched_barrier(0); }
;             }
.LSPs_top:
	s_cmpk_gt_u32 s79, 29
	s_cbranch_scc1 .LSPs_t0
	s_waitcnt vmcnt(8) lgkmcnt(0)
	s_barrier
.LSPs_t0d:
	s_cmpk_gt_u32 s79, 28
	s_cbranch_scc1 .LSPs_skipk
	s_add_i32 s98, s78, 0x8000
	s_and_b32 s98, s98, 0x18000
	s_add_i32 s98, s98, s29
	s_mov_b32 m0, s98
	v_lshl_add_u64 v[82:83], v[174:175], 0, s[40:41]
	global_load_lds_dwordx4 v[174:175], off
	s_add_i32 m0, s98, 0x2000
	s_nop 0
	global_load_lds_dwordx4 v[82:83], off
.LSPs_skipk:
	s_cmpk_gt_u32 s79, 29
	s_cbranch_scc1 .LSPs_skipv
	s_and_b32 s98, s78, 0x18000
	s_add_i32 s98, s98, s29
	s_add_i32 m0, s98, 0x4000
	v_lshl_add_u64 v[82:83], v[172:173], 0, s[40:41]
	global_load_lds_dwordx4 v[172:173], off
	s_add_i32 m0, s98, 0x6000
	s_nop 0
	global_load_lds_dwordx4 v[82:83], off
.LSPs_skipv:
.LSPs_scal:
	s_cmp_lt_u32 s76, s33
	s_cselect_b64 s[64:65], -1, 0
	s_cmp_gt_i32 s76, s67
	s_cselect_b64 s[80:81], -1, 0
	s_and_b64 s[64:65], s[64:65], s[80:81]
	s_cmp_gt_u32 s76, s28
	s_cselect_b32 s80, s31, s30
	v_mov_b32_e32 v82, s80
	v_cndmask_b32_e64 v98, v82, 0, s[64:65]
	v_cmp_eq_f32_e32 vcc, v98, v202
	s_nop 1
	s_and_b64 vcc, exec, vcc
	s_cbranch_vccz .LSPs_cin
.LSPs_qk:
	s_add_i32 s80, s78, 0xffff0000
	s_and_b32 s80, s80, 0x18000
	s_add_i32 s99, s78, 0xfffe8000
	s_and_b32 s99, s99, 0x18000
	v_add3_u32 v203, s80, v178, v162
	ds_read_b128 v[130:133], v203
	ds_read_b128 v[134:137], v203 offset:4096
	v_add3_u32 v203, s80, v180, v162
	ds_read_b128 v[138:141], v203
	ds_read_b128 v[142:145], v203 offset:4096
	v_add3_u32 v203, s80, v182, v162
	ds_read_b128 v[146:149], v203
	ds_read_b128 v[150:153], v203 offset:4096
	v_add3_u32 v203, s80, v184, v162
	ds_read_b128 v[158:161], v203
	ds_read_b128 v[204:207], v203 offset:4096
	s_waitcnt lgkmcnt(0)
	v_mfma_f32_32x32x16_bf16 v[98:113], v[130:133], v[126:129], v[66:81]
	v_mfma_f32_32x32x16_bf16 v[82:97], v[134:137], v[126:129], v[66:81]
	v_mfma_f32_32x32x16_bf16 v[98:113], v[138:141], v[122:125], v[98:113]
	v_mfma_f32_32x32x16_bf16 v[82:97], v[142:145], v[122:125], v[82:97]
	v_mfma_f32_32x32x16_bf16 v[98:113], v[146:149], v[118:121], v[98:113]
	v_mfma_f32_32x32x16_bf16 v[82:97], v[150:153], v[118:121], v[82:97]
	v_mfma_f32_32x32x16_bf16 v[98:113], v[158:161], v[114:117], v[98:113]
	v_mfma_f32_32x32x16_bf16 v[82:97], v[204:207], v[114:117], v[82:97]
	v_add3_u32 v236, s99, v179, v187
	ds_read_b128 v[146:149], v236 offset:16384
	ds_read_b128 v[150:153], v236 offset:20480
	ds_read_b128 v[154:157], v236 offset:24576
	ds_read_b128 v[158:161], v236 offset:28672
	v_add3_u32 v237, s99, v181, v187
	ds_read_b128 v[130:133], v237 offset:16384
	ds_read_b128 v[134:137], v237 offset:20480
	ds_read_b128 v[138:141], v237 offset:24576
	ds_read_b128 v[142:145], v237 offset:28672
	s_nop 1
	s_andn2_b64 vcc, exec, s[64:65]
	s_cbranch_vccnz .LSPs_max
	v_add_u32_e32 v203, s77, v171
	v_add_u32_e32 v204, 0x23b80, v203
	v_add_u32_e32 v206, 0x23c00, v203
	v_add_u32_e32 v210, 0x23c08, v203
	v_add_u32_e32 v208, 0x23b88, v203
	v_add_u32_e32 v218, 0x23c10, v203
	v_add_u32_e32 v212, 0x23b90, v203
	v_add_u32_e32 v216, 0x23c18, v203
	v_add_u32_e32 v214, 0x23b98, v203
	ds_read2_b32 v[204:205], v204 offset1:1
	ds_read2_b32 v[206:207], v206 offset1:1
	ds_read2_b32 v[208:209], v208 offset1:1
	ds_read2_b32 v[210:211], v210 offset1:1
	ds_read2_b32 v[212:213], v212 offset1:1
	ds_read2_b32 v[214:215], v214 offset1:1
	ds_read2_b32 v[216:217], v216 offset1:1
	ds_read2_b32 v[218:219], v218 offset1:1
	v_add_u32_e32 v220, 0x23bc0, v203
	v_add_u32_e32 v222, 0x23c40, v203
	v_add_u32_e32 v226, 0x23c48, v203
	v_add_u32_e32 v224, 0x23bc8, v203
	v_add_u32_e32 v228, 0x23bd0, v203
	v_add_u32_e32 v234, 0x23c58, v203
	ds_read2_b32 v[220:221], v220 offset1:1
	ds_read2_b32 v[222:223], v222 offset1:1
	ds_read2_b32 v[224:225], v224 offset1:1
	ds_read2_b32 v[226:227], v226 offset1:1
	v_add_u32_e32 v231, 0x23c50, v203
	v_add_u32_e32 v203, 0x23bd8, v203
	ds_read2_b32 v[228:229], v228 offset1:1
	ds_read2_b32 v[232:233], v203 offset1:1
	ds_read2_b32 v[234:235], v234 offset1:1
	ds_read2_b32 v[236:237], v231 offset1:1
	s_waitcnt lgkmcnt(10)
	v_pk_add_f32 v[104:105], v[104:105], v[214:215]
	v_pk_add_f32 v[102:103], v[102:103], v[212:213]
	v_pk_add_f32 v[100:101], v[100:101], v[208:209]
	s_waitcnt lgkmcnt(2)
	v_pk_add_f32 v[112:113], v[112:113], v[232:233]
	v_pk_add_f32 v[110:111], v[110:111], v[228:229]
	v_pk_add_f32 v[108:109], v[108:109], v[224:225]
	v_pk_add_f32 v[106:107], v[106:107], v[220:221]
	v_pk_add_f32 v[98:99], v[98:99], v[204:205]
	v_pk_add_f32 v[88:89], v[88:89], v[216:217]
	v_pk_add_f32 v[86:87], v[86:87], v[218:219]
	v_pk_add_f32 v[84:85], v[84:85], v[210:211]
	s_waitcnt lgkmcnt(1)
	v_pk_add_f32 v[96:97], v[96:97], v[234:235]
	s_waitcnt lgkmcnt(0)
	v_pk_add_f32 v[94:95], v[94:95], v[236:237]
	v_pk_add_f32 v[92:93], v[92:93], v[226:227]
	v_pk_add_f32 v[90:91], v[90:91], v[222:223]
	v_pk_add_f32 v[82:83], v[82:83], v[206:207]
; #define MX3(a, b, c) __builtin_fmaxf(__builtin_fmaxf((a), (b)), (c))
; template <bool WIN> ...
;     ...
;             float mxa = MX3(s0[0], s0[1], s1[0]), mxb = MX3(s0[2], s0[3], s1[1]);
;             mxa = MX3(mxa, s1[2], s1[3]);
; #pragma unroll
;             for (int r = 4; r < 16; r += 4) { mxa = MX3(mxa, s0[r], s0[r + 1]); mxb = MX3(mxb, s0[r + 2], s0[r + 3]); mxa = MX3(mxa, s1[r], s1[r + 1]); mxb = MX3(mxb, s1[r + 2], s1[r + 3]); }
;     ...
;             float mx = fmaxf(mxa, mxb);
;             if (__any(mx > THR)) {
;                 mx = fmaxf(mx, __shfl_xor(mx, 32));
;                 const float dl = fmaxf(mx, 0.f);
;                 m_ref += dl;
;                 const float f = __builtin_amdgcn_exp2f(-dl);
;                 l_run *= f;
; #pragma unroll
;                 for (int db = 0; db < NDB; ++db)
; #pragma unroll
;                     for (int r = 0; r < 16; ++r) o[db][r] *= f;
; #pragma unroll
;                 for (int r = 0; r < 16; ++r) { s0[r] -= dl; s1[r] -= dl; cvec[r] = cbase - m_ref; }
;             }
.LSPs_max:
	s_nop 0
	v_max_f32_e32 v203, v99, v99
	v_max_f32_e32 v204, v98, v98
	v_max_f32_e32 v203, v204, v203
	s_nop 5
	v_max3_f32 v204, v100, v101, v83
	v_max3_f32 v203, v203, v82, v84
	v_max3_f32 v203, v203, v85, v102
	v_max3_f32 v204, v204, v104, v105
	v_max3_f32 v203, v203, v103, v86
	v_max3_f32 v204, v204, v88, v89
	v_max3_f32 v203, v203, v87, v106
	v_max3_f32 v204, v204, v108, v109
	v_max3_f32 v203, v203, v107, v90
	v_max3_f32 v204, v204, v92, v93
	v_max3_f32 v203, v203, v91, v110
	v_max3_f32 v204, v204, v112, v113
	v_max3_f32 v203, v203, v111, v94
	v_max3_f32 v204, v204, v96, v97
	v_max3_f32 v203, v203, v95, v204
	v_cmp_lt_f32_e32 vcc, s24, v203
	s_cbranch_vccz .LSPs_pv
	s_cmp_eq_u32 s79, 0
	s_cbranch_scc1 .LSPs_rnopv
	s_waitcnt lgkmcnt(0)
	v_add3_u32 v236, s99, v179, v187
	ds_read_b128 v[146:149], v236 offset:16384
	ds_read_b128 v[150:153], v236 offset:20480
	ds_read_b128 v[154:157], v236 offset:24576
	ds_read_b128 v[158:161], v236 offset:28672
	v_add3_u32 v237, s99, v181, v187
	ds_read_b128 v[130:133], v237 offset:16384
	ds_read_b128 v[134:137], v237 offset:20480
	ds_read_b128 v[138:141], v237 offset:24576
	ds_read_b128 v[142:145], v237 offset:28672
	s_waitcnt lgkmcnt(4)
	v_mfma_f32_32x32x16_bf16 v[50:65], v[146:149], v[238:241], v[50:65]
	v_mfma_f32_32x32x16_bf16 v[34:49], v[150:153], v[238:241], v[34:49]
	v_mfma_f32_32x32x16_bf16 v[18:33], v[154:157], v[238:241], v[18:33]
	v_mfma_f32_32x32x16_bf16 v[2:17], v[158:161], v[238:241], v[2:17]
	v_add3_u32 v236, s99, v183, v187
	ds_read_b128 v[146:149], v236 offset:16384
	ds_read_b128 v[150:153], v236 offset:20480
	ds_read_b128 v[154:157], v236 offset:24576
	ds_read_b128 v[158:161], v236 offset:28672
	s_waitcnt lgkmcnt(4)
	v_mfma_f32_32x32x16_bf16 v[50:65], v[130:133], v[242:245], v[50:65]
	v_mfma_f32_32x32x16_bf16 v[34:49], v[134:137], v[242:245], v[34:49]
	v_mfma_f32_32x32x16_bf16 v[18:33], v[138:141], v[242:245], v[18:33]
	v_mfma_f32_32x32x16_bf16 v[2:17], v[142:145], v[242:245], v[2:17]
	v_add3_u32 v237, s99, v190, v187
	ds_read_b128 v[130:133], v237 offset:16384
	ds_read_b128 v[134:137], v237 offset:20480
	ds_read_b128 v[138:141], v237 offset:24576
	ds_read_b128 v[142:145], v237 offset:28672
	s_waitcnt lgkmcnt(4)
	v_mfma_f32_32x32x16_bf16 v[50:65], v[146:149], v[246:249], v[50:65]
	v_mfma_f32_32x32x16_bf16 v[34:49], v[150:153], v[246:249], v[34:49]
	v_mfma_f32_32x32x16_bf16 v[18:33], v[154:157], v[246:249], v[18:33]
	v_mfma_f32_32x32x16_bf16 v[2:17], v[158:161], v[246:249], v[2:17]
	s_waitcnt lgkmcnt(0)
	v_mfma_f32_32x32x16_bf16 v[50:65], v[130:133], v[250:253], v[50:65]
	v_mfma_f32_32x32x16_bf16 v[34:49], v[134:137], v[250:253], v[34:49]
	v_mfma_f32_32x32x16_bf16 v[18:33], v[138:141], v[250:253], v[18:33]
	v_mfma_f32_32x32x16_bf16 v[2:17], v[142:145], v[250:253], v[2:17]
	s_nop 7
	s_nop 7
.LSPs_rnopv:
	ds_bpermute_b32 v66, v176, v203
	s_waitcnt lgkmcnt(0)
	v_max3_f32 v68, v203, v66, 0
	v_exp_f32_e64 v70, -v68
	v_add_f32_e32 v201, v201, v68
	v_sub_f32_e32 v66, v202, v201
	v_pk_add_f32 v[98:99], v[98:99], v[68:69] op_sel_hi:[1,0] neg_lo:[0,1] neg_hi:[0,1]
	v_pk_mul_f32 v[64:65], v[64:65], v[70:71] op_sel_hi:[1,0]
	v_pk_mul_f32 v[62:63], v[62:63], v[70:71] op_sel_hi:[1,0]
	v_pk_mul_f32 v[60:61], v[60:61], v[70:71] op_sel_hi:[1,0]
	v_pk_mul_f32 v[58:59], v[58:59], v[70:71] op_sel_hi:[1,0]
	v_pk_mul_f32 v[56:57], v[56:57], v[70:71] op_sel_hi:[1,0]
	v_pk_mul_f32 v[54:55], v[54:55], v[70:71] op_sel_hi:[1,0]
	v_pk_mul_f32 v[52:53], v[52:53], v[70:71] op_sel_hi:[1,0]
	v_pk_mul_f32 v[50:51], v[50:51], v[70:71] op_sel_hi:[1,0]
	v_pk_mul_f32 v[48:49], v[48:49], v[70:71] op_sel_hi:[1,0]
	v_pk_mul_f32 v[46:47], v[46:47], v[70:71] op_sel_hi:[1,0]
	v_pk_mul_f32 v[44:45], v[44:45], v[70:71] op_sel_hi:[1,0]
	v_pk_mul_f32 v[42:43], v[42:43], v[70:71] op_sel_hi:[1,0]
	v_pk_mul_f32 v[40:41], v[40:41], v[70:71] op_sel_hi:[1,0]
	v_pk_mul_f32 v[38:39], v[38:39], v[70:71] op_sel_hi:[1,0]
	v_pk_mul_f32 v[36:37], v[36:37], v[70:71] op_sel_hi:[1,0]
	v_pk_mul_f32 v[34:35], v[34:35], v[70:71] op_sel_hi:[1,0]
	v_pk_mul_f32 v[32:33], v[32:33], v[70:71] op_sel_hi:[1,0]
	v_pk_mul_f32 v[30:31], v[30:31], v[70:71] op_sel_hi:[1,0]
	v_pk_mul_f32 v[28:29], v[28:29], v[70:71] op_sel_hi:[1,0]
	v_pk_mul_f32 v[26:27], v[26:27], v[70:71] op_sel_hi:[1,0]
	v_pk_mul_f32 v[24:25], v[24:25], v[70:71] op_sel_hi:[1,0]
	v_pk_mul_f32 v[22:23], v[22:23], v[70:71] op_sel_hi:[1,0]
	v_pk_mul_f32 v[20:21], v[20:21], v[70:71] op_sel_hi:[1,0]
	v_pk_mul_f32 v[18:19], v[18:19], v[70:71] op_sel_hi:[1,0]
	v_pk_mul_f32 v[16:17], v[16:17], v[70:71] op_sel_hi:[1,0]
	v_pk_mul_f32 v[14:15], v[14:15], v[70:71] op_sel_hi:[1,0]
	v_pk_mul_f32 v[12:13], v[12:13], v[70:71] op_sel_hi:[1,0]
	v_pk_mul_f32 v[10:11], v[10:11], v[70:71] op_sel_hi:[1,0]
	v_pk_mul_f32 v[8:9], v[8:9], v[70:71] op_sel_hi:[1,0]
	v_pk_mul_f32 v[6:7], v[6:7], v[70:71] op_sel_hi:[1,0]
	v_pk_mul_f32 v[4:5], v[4:5], v[70:71] op_sel_hi:[1,0]
	v_pk_mul_f32 v[2:3], v[2:3], v[70:71] op_sel_hi:[1,0]
	v_pk_add_f32 v[82:83], v[82:83], v[68:69] op_sel_hi:[1,0] neg_lo:[0,1] neg_hi:[0,1]
	v_pk_add_f32 v[100:101], v[100:101], v[68:69] op_sel_hi:[1,0] neg_lo:[0,1] neg_hi:[0,1]
	v_pk_add_f32 v[84:85], v[84:85], v[68:69] op_sel_hi:[1,0] neg_lo:[0,1] neg_hi:[0,1]
	v_pk_add_f32 v[102:103], v[102:103], v[68:69] op_sel_hi:[1,0] neg_lo:[0,1] neg_hi:[0,1]
	v_pk_add_f32 v[86:87], v[86:87], v[68:69] op_sel_hi:[1,0] neg_lo:[0,1] neg_hi:[0,1]
	v_pk_add_f32 v[104:105], v[104:105], v[68:69] op_sel_hi:[1,0] neg_lo:[0,1] neg_hi:[0,1]
	v_pk_add_f32 v[88:89], v[88:89], v[68:69] op_sel_hi:[1,0] neg_lo:[0,1] neg_hi:[0,1]
	v_pk_add_f32 v[106:107], v[106:107], v[68:69] op_sel_hi:[1,0] neg_lo:[0,1] neg_hi:[0,1]
	v_pk_add_f32 v[90:91], v[90:91], v[68:69] op_sel_hi:[1,0] neg_lo:[0,1] neg_hi:[0,1]
	v_pk_add_f32 v[108:109], v[108:109], v[68:69] op_sel_hi:[1,0] neg_lo:[0,1] neg_hi:[0,1]
	v_pk_add_f32 v[92:93], v[92:93], v[68:69] op_sel_hi:[1,0] neg_lo:[0,1] neg_hi:[0,1]
	v_pk_add_f32 v[110:111], v[110:111], v[68:69] op_sel_hi:[1,0] neg_lo:[0,1] neg_hi:[0,1]
	v_pk_add_f32 v[94:95], v[94:95], v[68:69] op_sel_hi:[1,0] neg_lo:[0,1] neg_hi:[0,1]
	v_pk_add_f32 v[112:113], v[112:113], v[68:69] op_sel_hi:[1,0] neg_lo:[0,1] neg_hi:[0,1]
	v_pk_add_f32 v[96:97], v[96:97], v[68:69] op_sel_hi:[1,0] neg_lo:[0,1] neg_hi:[0,1]
	v_mul_f32_e32 v0, v0, v70
	v_mov_b32_e32 v67, v66
	v_mov_b32_e32 v68, v66
	v_mov_b32_e32 v69, v66
	v_mov_b32_e32 v70, v66
	v_mov_b32_e32 v71, v66
	v_mov_b32_e32 v72, v66
	v_mov_b32_e32 v73, v66
	v_mov_b32_e32 v74, v66
	v_mov_b32_e32 v75, v66
	v_mov_b32_e32 v76, v66
	v_mov_b32_e32 v77, v66
	v_mov_b32_e32 v78, v66
	v_mov_b32_e32 v79, v66
	v_mov_b32_e32 v80, v66
	v_mov_b32_e32 v81, v66
	s_branch .LSPs_pure
; #define ALAS __attribute__((address_space(3)))
; template <bool WIN> ...
;     ...
;             float ls0 = 0.f, ls1 = 0.f;
;     ...
;             union PFU { u32x4 u; bf16x8 b; };
;             PFU p0, p1, p2, p3;
;             AT_EXP(s0, 0, p0);
; #pragma unroll
;             for (int kk = 0; kk < 2; ++kk)
; #pragma unroll
;                 for (int db = 0; db < NDB; ++db) vc[kk * NDB + db] = *(const ALAS bf16x8*)(sb + vx[kk + 2] + db * 4096);
;             __builtin_amdgcn_sched_barrier(0);
; #pragma unroll
;             for (int db = 0; db < NDB; ++db) o[db] = __builtin_amdgcn_mfma_f32_32x32x16_bf16(va[db], p0.b, o[db], 0, 0, 0);
;             AT_EXP(s0, 8, p1);
;             __builtin_amdgcn_sched_barrier(0);
; #pragma unroll
;             for (int db = 0; db < NDB; ++db) o[db] = __builtin_amdgcn_mfma_f32_32x32x16_bf16(va[NDB + db], p1.b, o[db], 0, 0, 0);
;             AT_EXP(s1, 0, p2);
;             __builtin_amdgcn_sched_barrier(0);
; #pragma unroll
;             for (int db = 0; db < NDB; ++db) o[db] = __builtin_amdgcn_mfma_f32_32x32x16_bf16(vc[db], p2.b, o[db], 0, 0, 0);
;             AT_EXP(s1, 8, p3);
;             __builtin_amdgcn_sched_barrier(0);
; #pragma unroll
;             for (int db = 0; db < NDB; ++db) o[db] = __builtin_amdgcn_mfma_f32_32x32x16_bf16(vc[NDB + db], p3.b, o[db], 0, 0, 0);
;             __builtin_amdgcn_sched_barrier(0);
;     ...
;             l_run += ls0 + ls1;
.LSPs_pv:
	s_cmp_eq_u32 s79, 0
	s_cbranch_scc1 .LSPs_pure
	v_mov_b32_e32 v228, 0
	v_mov_b32_e32 v229, 0
	s_waitcnt lgkmcnt(4)
	v_mfma_f32_32x32x16_bf16 v[50:65], v[146:149], v[238:241], v[50:65]
	v_exp_f32_e32 v98, v98
	v_exp_f32_e32 v99, v99
	v_mfma_f32_32x32x16_bf16 v[34:49], v[150:153], v[238:241], v[34:49]
	v_exp_f32_e32 v100, v100
	v_exp_f32_e32 v101, v101
	v_add_f32_e32 v228, v228, v98
	v_add_f32_e32 v229, v229, v99
	v_mfma_f32_32x32x16_bf16 v[18:33], v[154:157], v[238:241], v[18:33]
	v_exp_f32_e32 v102, v102
	v_exp_f32_e32 v103, v103
	v_add_f32_e32 v228, v228, v100
	v_add_f32_e32 v229, v229, v101
	v_mfma_f32_32x32x16_bf16 v[2:17], v[158:161], v[238:241], v[2:17]
	v_exp_f32_e32 v104, v104
	v_exp_f32_e32 v105, v105
	v_add_f32_e32 v228, v228, v102
	v_add_f32_e32 v229, v229, v103
	v_add3_u32 v236, s99, v183, v187
	ds_read_b128 v[146:149], v236 offset:16384
	ds_read_b128 v[150:153], v236 offset:20480
	ds_read_b128 v[154:157], v236 offset:24576
	ds_read_b128 v[158:161], v236 offset:28672
	s_waitcnt lgkmcnt(4)
	v_mfma_f32_32x32x16_bf16 v[50:65], v[130:133], v[242:245], v[50:65]
	v_exp_f32_e32 v106, v106
	v_exp_f32_e32 v107, v107
	v_add_f32_e32 v228, v228, v104
	v_add_f32_e32 v229, v229, v105
	v_cvt_pk_bf16_f32 v238, v98, v99
	v_mfma_f32_32x32x16_bf16 v[34:49], v[134:137], v[242:245], v[34:49]
	v_exp_f32_e32 v108, v108
	v_exp_f32_e32 v109, v109
	v_add_f32_e32 v228, v228, v106
	v_add_f32_e32 v229, v229, v107
	v_cvt_pk_bf16_f32 v239, v100, v101
	v_mfma_f32_32x32x16_bf16 v[18:33], v[138:141], v[242:245], v[18:33]
	v_exp_f32_e32 v110, v110
	v_exp_f32_e32 v111, v111
	v_add_f32_e32 v228, v228, v108
	v_add_f32_e32 v229, v229, v109
	v_cvt_pk_bf16_f32 v240, v102, v103
	v_mfma_f32_32x32x16_bf16 v[2:17], v[142:145], v[242:245], v[2:17]
	v_exp_f32_e32 v112, v112
	v_exp_f32_e32 v113, v113
	v_add_f32_e32 v228, v228, v110
	v_add_f32_e32 v229, v229, v111
	v_cvt_pk_bf16_f32 v241, v104, v105
	v_add3_u32 v237, s99, v190, v187
	ds_read_b128 v[130:133], v237 offset:16384
	ds_read_b128 v[134:137], v237 offset:20480
	ds_read_b128 v[138:141], v237 offset:24576
	ds_read_b128 v[142:145], v237 offset:28672
	s_waitcnt lgkmcnt(4)
	v_mfma_f32_32x32x16_bf16 v[50:65], v[146:149], v[246:249], v[50:65]
	v_exp_f32_e32 v82, v82
	v_exp_f32_e32 v83, v83
	v_add_f32_e32 v228, v228, v112
	v_add_f32_e32 v229, v229, v113
	v_cvt_pk_bf16_f32 v242, v106, v107
	v_mfma_f32_32x32x16_bf16 v[34:49], v[150:153], v[246:249], v[34:49]
	v_exp_f32_e32 v84, v84
	v_exp_f32_e32 v85, v85
	v_add_f32_e32 v228, v228, v82
	v_add_f32_e32 v229, v229, v83
	v_cvt_pk_bf16_f32 v243, v108, v109
	v_mfma_f32_32x32x16_bf16 v[18:33], v[154:157], v[246:249], v[18:33]
	v_exp_f32_e32 v86, v86
	v_exp_f32_e32 v87, v87
	v_add_f32_e32 v228, v228, v84
	v_add_f32_e32 v229, v229, v85
	v_cvt_pk_bf16_f32 v244, v110, v111
	v_mfma_f32_32x32x16_bf16 v[2:17], v[158:161], v[246:249], v[2:17]
	v_exp_f32_e32 v88, v88
	v_exp_f32_e32 v89, v89
	v_add_f32_e32 v228, v228, v86
	v_add_f32_e32 v229, v229, v87
	v_cvt_pk_bf16_f32 v245, v112, v113
	s_waitcnt lgkmcnt(0)
	v_mfma_f32_32x32x16_bf16 v[50:65], v[130:133], v[250:253], v[50:65]
	v_exp_f32_e32 v90, v90
	v_exp_f32_e32 v91, v91
	v_add_f32_e32 v228, v228, v88
	v_add_f32_e32 v229, v229, v89
	v_cvt_pk_bf16_f32 v246, v82, v83
	v_mfma_f32_32x32x16_bf16 v[34:49], v[134:137], v[250:253], v[34:49]
	v_exp_f32_e32 v92, v92
	v_exp_f32_e32 v93, v93
	v_add_f32_e32 v228, v228, v90
	v_add_f32_e32 v229, v229, v91
	v_cvt_pk_bf16_f32 v247, v84, v85
	v_mfma_f32_32x32x16_bf16 v[18:33], v[138:141], v[250:253], v[18:33]
	v_exp_f32_e32 v94, v94
	v_exp_f32_e32 v95, v95
	v_add_f32_e32 v228, v228, v92
	v_add_f32_e32 v229, v229, v93
	v_cvt_pk_bf16_f32 v248, v86, v87
	v_mfma_f32_32x32x16_bf16 v[2:17], v[142:145], v[250:253], v[2:17]
	v_exp_f32_e32 v96, v96
	v_exp_f32_e32 v97, v97
	v_add_f32_e32 v228, v228, v94
	v_add_f32_e32 v229, v229, v95
	v_cvt_pk_bf16_f32 v249, v88, v89
	v_add_f32_e32 v228, v228, v96
	v_add_f32_e32 v229, v229, v97
	v_cvt_pk_bf16_f32 v250, v90, v91
	v_cvt_pk_bf16_f32 v251, v92, v93
	v_cvt_pk_bf16_f32 v252, v94, v95
	v_cvt_pk_bf16_f32 v253, v96, v97
	v_add_f32_e32 v228, v228, v229
	s_add_i32 s79, s79, 1
	s_add_i32 s78, s78, 0x8000
	s_addk_i32 s77, 0x100
	s_add_i32 s76, s76, 64
	v_add_f32_e32 v0, v0, v228
	v_lshl_add_u64 v[172:173], v[172:173], 0, s[48:49]
	s_cmpk_eq_i32 s77, 0x2000
	v_lshl_add_u64 v[174:175], v[174:175], 0, s[60:61]
	s_cbranch_scc0 .LSPs_top
	s_branch .LSPs_exit
; #define ALAS __attribute__((address_space(3)))
; template <bool WIN> ...
;     ...
;             float ls0 = 0.f, ls1 = 0.f;
;     ...
;             union PFU { u32x4 u; bf16x8 b; };
;             PFU p0, p1, p2, p3;
;             AT_EXP(s0, 0, p0);
; #pragma unroll
;             for (int kk = 0; kk < 2; ++kk)
; #pragma unroll
;                 for (int db = 0; db < NDB; ++db) vc[kk * NDB + db] = *(const ALAS bf16x8*)(sb + vx[kk + 2] + db * 4096);
;             __builtin_amdgcn_sched_barrier(0);
; #pragma unroll
;             for (int db = 0; db < NDB; ++db) o[db] = __builtin_amdgcn_mfma_f32_32x32x16_bf16(va[db], p0.b, o[db], 0, 0, 0);
;             AT_EXP(s0, 8, p1);
;             __builtin_amdgcn_sched_barrier(0);
; #pragma unroll
;             for (int db = 0; db < NDB; ++db) o[db] = __builtin_amdgcn_mfma_f32_32x32x16_bf16(va[NDB + db], p1.b, o[db], 0, 0, 0);
;             AT_EXP(s1, 0, p2);
;             __builtin_amdgcn_sched_barrier(0);
; #pragma unroll
;             for (int db = 0; db < NDB; ++db) o[db] = __builtin_amdgcn_mfma_f32_32x32x16_bf16(vc[db], p2.b, o[db], 0, 0, 0);
;             AT_EXP(s1, 8, p3);
;             __builtin_amdgcn_sched_barrier(0);
; #pragma unroll
;             for (int db = 0; db < NDB; ++db) o[db] = __builtin_amdgcn_mfma_f32_32x32x16_bf16(vc[NDB + db], p3.b, o[db], 0, 0, 0);
;             __builtin_amdgcn_sched_barrier(0);
;     ...
;             l_run += ls0 + ls1;
.LSPs_pure:
	v_exp_f32_e32 v98, v98
	v_exp_f32_e32 v99, v99
	v_exp_f32_e32 v100, v100
	v_exp_f32_e32 v101, v101
	v_exp_f32_e32 v102, v102
	v_exp_f32_e32 v103, v103
	v_exp_f32_e32 v104, v104
	v_exp_f32_e32 v105, v105
	v_cvt_pk_bf16_f32 v238, v98, v99
	v_cvt_pk_bf16_f32 v239, v100, v101
	v_cvt_pk_bf16_f32 v240, v102, v103
	v_cvt_pk_bf16_f32 v241, v104, v105
	v_mov_b32_e32 v228, v98
	v_mov_b32_e32 v229, v102
	v_add_f32_e32 v228, v228, v99
	v_add_f32_e32 v229, v229, v103
	v_add_f32_e32 v228, v228, v100
	v_add_f32_e32 v229, v229, v104
	v_add_f32_e32 v228, v228, v101
	v_add_f32_e32 v229, v229, v105
	v_exp_f32_e32 v106, v106
	v_exp_f32_e32 v107, v107
	v_exp_f32_e32 v108, v108
	v_exp_f32_e32 v109, v109
	v_exp_f32_e32 v110, v110
	v_exp_f32_e32 v111, v111
	v_exp_f32_e32 v112, v112
	v_exp_f32_e32 v113, v113
	v_cvt_pk_bf16_f32 v242, v106, v107
	v_cvt_pk_bf16_f32 v243, v108, v109
	v_cvt_pk_bf16_f32 v244, v110, v111
	v_cvt_pk_bf16_f32 v245, v112, v113
	v_add_f32_e32 v228, v228, v106
	v_add_f32_e32 v229, v229, v110
	v_add_f32_e32 v228, v228, v107
	v_add_f32_e32 v229, v229, v111
	v_add_f32_e32 v228, v228, v108
	v_add_f32_e32 v229, v229, v112
	v_add_f32_e32 v228, v228, v109
	v_add_f32_e32 v229, v229, v113
	v_exp_f32_e32 v82, v82
	v_exp_f32_e32 v83, v83
	v_exp_f32_e32 v84, v84
	v_exp_f32_e32 v85, v85
	v_exp_f32_e32 v86, v86
	v_exp_f32_e32 v87, v87
	v_exp_f32_e32 v88, v88
	v_exp_f32_e32 v89, v89
	v_cvt_pk_bf16_f32 v246, v82, v83
	v_cvt_pk_bf16_f32 v247, v84, v85
	v_cvt_pk_bf16_f32 v248, v86, v87
	v_cvt_pk_bf16_f32 v249, v88, v89
	v_add_f32_e32 v228, v228, v82
	v_add_f32_e32 v229, v229, v86
	v_add_f32_e32 v228, v228, v83
	v_add_f32_e32 v229, v229, v87
	v_add_f32_e32 v228, v228, v84
	v_add_f32_e32 v229, v229, v88
	v_add_f32_e32 v228, v228, v85
	v_add_f32_e32 v229, v229, v89
	v_exp_f32_e32 v90, v90
	v_exp_f32_e32 v91, v91
	v_exp_f32_e32 v92, v92
	v_exp_f32_e32 v93, v93
	v_exp_f32_e32 v94, v94
	v_exp_f32_e32 v95, v95
	v_exp_f32_e32 v96, v96
	v_exp_f32_e32 v97, v97
	v_cvt_pk_bf16_f32 v250, v90, v91
	v_cvt_pk_bf16_f32 v251, v92, v93
	v_cvt_pk_bf16_f32 v252, v94, v95
	v_cvt_pk_bf16_f32 v253, v96, v97
	v_add_f32_e32 v228, v228, v90
	v_add_f32_e32 v229, v229, v94
	v_add_f32_e32 v228, v228, v91
	v_add_f32_e32 v229, v229, v95
	v_add_f32_e32 v228, v228, v92
	v_add_f32_e32 v229, v229, v96
	v_add_f32_e32 v228, v228, v93
	v_add_f32_e32 v229, v229, v97
	v_add_f32_e32 v228, v228, v229
	s_add_i32 s79, s79, 1
	s_add_i32 s78, s78, 0x8000
	s_addk_i32 s77, 0x100
	s_add_i32 s76, s76, 64
	v_add_f32_e32 v0, v0, v228
	v_lshl_add_u64 v[172:173], v[172:173], 0, s[48:49]
	s_cmpk_eq_i32 s77, 0x2000
	v_lshl_add_u64 v[174:175], v[174:175], 0, s[60:61]
	s_cbranch_scc0 .LSPs_top
	s_branch .LSPs_exit
.LSPs_exit:
	s_add_i32 s99, s78, 0xfffe8000
	s_and_b32 s99, s99, 0x18000
	v_add3_u32 v236, s99, v179, v187
	ds_read_b128 v[146:149], v236 offset:16384
	ds_read_b128 v[150:153], v236 offset:20480
	ds_read_b128 v[154:157], v236 offset:24576
	ds_read_b128 v[158:161], v236 offset:28672
	v_add3_u32 v237, s99, v181, v187
	ds_read_b128 v[130:133], v237 offset:16384
	ds_read_b128 v[134:137], v237 offset:20480
	ds_read_b128 v[138:141], v237 offset:24576
	ds_read_b128 v[142:145], v237 offset:28672
	s_waitcnt lgkmcnt(4)
	v_mfma_f32_32x32x16_bf16 v[50:65], v[146:149], v[238:241], v[50:65]
	v_mfma_f32_32x32x16_bf16 v[34:49], v[150:153], v[238:241], v[34:49]
	v_mfma_f32_32x32x16_bf16 v[18:33], v[154:157], v[238:241], v[18:33]
	v_mfma_f32_32x32x16_bf16 v[2:17], v[158:161], v[238:241], v[2:17]
	v_add3_u32 v236, s99, v183, v187
	ds_read_b128 v[146:149], v236 offset:16384
	ds_read_b128 v[150:153], v236 offset:20480
	ds_read_b128 v[154:157], v236 offset:24576
	ds_read_b128 v[158:161], v236 offset:28672
	s_waitcnt lgkmcnt(4)
	v_mfma_f32_32x32x16_bf16 v[50:65], v[130:133], v[242:245], v[50:65]
	v_mfma_f32_32x32x16_bf16 v[34:49], v[134:137], v[242:245], v[34:49]
	v_mfma_f32_32x32x16_bf16 v[18:33], v[138:141], v[242:245], v[18:33]
	v_mfma_f32_32x32x16_bf16 v[2:17], v[142:145], v[242:245], v[2:17]
	v_add3_u32 v237, s99, v190, v187
	ds_read_b128 v[130:133], v237 offset:16384
	ds_read_b128 v[134:137], v237 offset:20480
	ds_read_b128 v[138:141], v237 offset:24576
	ds_read_b128 v[142:145], v237 offset:28672
	s_waitcnt lgkmcnt(4)
	v_mfma_f32_32x32x16_bf16 v[50:65], v[146:149], v[246:249], v[50:65]
	v_mfma_f32_32x32x16_bf16 v[34:49], v[150:153], v[246:249], v[34:49]
	v_mfma_f32_32x32x16_bf16 v[18:33], v[154:157], v[246:249], v[18:33]
	v_mfma_f32_32x32x16_bf16 v[2:17], v[158:161], v[246:249], v[2:17]
	s_waitcnt lgkmcnt(0)
	v_mfma_f32_32x32x16_bf16 v[50:65], v[130:133], v[250:253], v[50:65]
	v_mfma_f32_32x32x16_bf16 v[34:49], v[134:137], v[250:253], v[34:49]
	v_mfma_f32_32x32x16_bf16 v[18:33], v[138:141], v[250:253], v[18:33]
	v_mfma_f32_32x32x16_bf16 v[2:17], v[142:145], v[250:253], v[2:17]
	s_branch .LBB0_286

; template <bool WIN> ...
;     ...
;             const float cinit = near ? 0.f : (k0 > qw ? cfar_hi : cfar_lo);
;             if (__builtin_expect(cinit != cbase, 0)) { cbase = cinit; asm volatile("" ::: "memory");
; #pragma unroll
;                 for (int r = 0; r < 16; ++r) cvec[r] = cbase - m_ref; }
.LSPs_cin:
	v_sub_f32_e32 v82, v98, v201
	v_mov_b32_e32 v202, v98
	v_mov_b32_e32 v66, v82
	v_mov_b32_e32 v67, v82
	v_mov_b32_e32 v68, v82
	v_mov_b32_e32 v69, v82
	v_mov_b32_e32 v70, v82
	v_mov_b32_e32 v71, v82
	v_mov_b32_e32 v72, v82
	v_mov_b32_e32 v73, v82
	v_mov_b32_e32 v74, v82
	v_mov_b32_e32 v75, v82
	v_mov_b32_e32 v76, v82
	v_mov_b32_e32 v77, v82
	v_mov_b32_e32 v78, v82
	v_mov_b32_e32 v79, v82
	v_mov_b32_e32 v80, v82
	v_mov_b32_e32 v81, v82
	s_branch .LSPs_qk
